# stack6 + accumulator zeroing before every GEMM K-loop: 128 v_mov_b32 -> 64 v_pk_mov_b32 (16 instances)
# speedup vs baseline: 1.0050x; 1.0050x over previous
; template <class Epi, class Sched, bool ALIGN_EPI = false, bool SP2 = false, bool ABLK = false, bool BBLK = false>
; __device__ __forceinline__ void gemm_phase(PG8_LAS unsigned char* lds, const Gemm g, const Sched& S, const Epi& E) {
;     ...
;         const char* nA = has_next ? (const char*)g.A + (size_t)nxt.pm * tstepA : cA; const char* nB = has_next ? (const char*)g.Bt + (size_t)nxt.pn * tstepB : cB;
;         for (int t = 0; t < nt; t += 2) {
;             const bool last = (t == nt - 2);
;             const char* a1 = cA + (size_t)(t + 1) * kstepA;
;             const char* a2 = last ? nA : cA + (size_t)(t + 2) * kstepA; const char* b2 = last ? nB : cB + (size_t)(t + 2) * kstepB;
;             const char* a3 = a2 + kstepA; const char* b3 = b2 + kstepB;
;     ...
;         for (int a = 0; a < 2; ++a)
; #pragma unroll
;             for (int b = 0; b < 2; ++b)
; #pragma unroll
;                 for (int m = 0; m < 4; ++m)
; #pragma unroll
;                     for (int n = 0; n < 2; ++n) acc[a][b][m][n] = (f32x4){0.f, 0.f, 0.f, 0.f};
.LBB0_215:
	s_ashr_i32 s15, s14, 31
	s_lshl_b64 s[18:19], s[14:15], 20
	s_add_u32 s18, s35, s18
	s_addc_u32 s19, s36, s19
	s_and_b64 s[20:21], s[4:5], exec
	s_cselect_b32 s15, s19, s23
	s_cselect_b32 s65, s18, s22
	s_ashr_i32 s13, s12, 31
	s_lshl_b64 s[20:21], s[12:13], 20
	s_add_u32 s20, s37, s20
	s_addc_u32 s21, s40, s21
	s_and_b64 s[26:27], s[4:5], exec
	s_cselect_b32 s13, s21, s25
	s_cselect_b32 s68, s20, s24
	s_add_u32 s22, s22, 0xc000
	s_addc_u32 s23, s23, 0
	s_add_u32 s72, s24, 0x10000
	v_mov_b32_e32 v2, 0
	s_addc_u32 s73, s25, 0
	s_mov_b32 s81, -2
	v_pk_mov_b32 v[2:3], 0, 0
	v_pk_mov_b32 v[4:5], 0, 0
	v_pk_mov_b32 v[6:7], 0, 0
	v_pk_mov_b32 v[8:9], 0, 0
	v_pk_mov_b32 v[10:11], 0, 0
	v_pk_mov_b32 v[12:13], 0, 0
	v_pk_mov_b32 v[14:15], 0, 0
	v_pk_mov_b32 v[16:17], 0, 0
	v_pk_mov_b32 v[18:19], 0, 0
	v_pk_mov_b32 v[20:21], 0, 0
	v_pk_mov_b32 v[22:23], 0, 0
	v_pk_mov_b32 v[24:25], 0, 0
	v_pk_mov_b32 v[26:27], 0, 0
	v_pk_mov_b32 v[28:29], 0, 0
	v_pk_mov_b32 v[30:31], 0, 0
	v_pk_mov_b32 v[32:33], 0, 0
	v_pk_mov_b32 v[34:35], 0, 0
	v_pk_mov_b32 v[36:37], 0, 0
	v_pk_mov_b32 v[38:39], 0, 0
	v_pk_mov_b32 v[40:41], 0, 0
	v_pk_mov_b32 v[42:43], 0, 0
	v_pk_mov_b32 v[44:45], 0, 0
	v_pk_mov_b32 v[46:47], 0, 0
	v_pk_mov_b32 v[48:49], 0, 0
	v_pk_mov_b32 v[50:51], 0, 0
	v_pk_mov_b32 v[52:53], 0, 0
	v_pk_mov_b32 v[54:55], 0, 0
	v_pk_mov_b32 v[56:57], 0, 0
	v_pk_mov_b32 v[58:59], 0, 0
	v_pk_mov_b32 v[60:61], 0, 0
	v_pk_mov_b32 v[62:63], 0, 0
	v_pk_mov_b32 v[64:65], 0, 0
	v_pk_mov_b32 v[66:67], 0, 0
	v_pk_mov_b32 v[68:69], 0, 0
	v_pk_mov_b32 v[70:71], 0, 0
	v_pk_mov_b32 v[72:73], 0, 0
	v_pk_mov_b32 v[74:75], 0, 0
	v_pk_mov_b32 v[76:77], 0, 0
	v_pk_mov_b32 v[78:79], 0, 0
	v_pk_mov_b32 v[80:81], 0, 0
	v_pk_mov_b32 v[82:83], 0, 0
	v_pk_mov_b32 v[84:85], 0, 0
	v_pk_mov_b32 v[86:87], 0, 0
	v_pk_mov_b32 v[88:89], 0, 0
	v_pk_mov_b32 v[90:91], 0, 0
	v_pk_mov_b32 v[92:93], 0, 0
	v_pk_mov_b32 v[94:95], 0, 0
	v_pk_mov_b32 v[96:97], 0, 0
	v_pk_mov_b32 v[98:99], 0, 0
	v_pk_mov_b32 v[100:101], 0, 0
	v_pk_mov_b32 v[102:103], 0, 0
	v_pk_mov_b32 v[104:105], 0, 0
	v_pk_mov_b32 v[106:107], 0, 0
	v_pk_mov_b32 v[108:109], 0, 0
	v_pk_mov_b32 v[110:111], 0, 0
	v_pk_mov_b32 v[112:113], 0, 0
	v_pk_mov_b32 v[114:115], 0, 0
	v_pk_mov_b32 v[116:117], 0, 0
	v_pk_mov_b32 v[118:119], 0, 0
	v_pk_mov_b32 v[120:121], 0, 0
	v_pk_mov_b32 v[122:123], 0, 0
	v_pk_mov_b32 v[124:125], 0, 0
	v_pk_mov_b32 v[126:127], 0, 0
	v_pk_mov_b32 v[128:129], 0, 0

; template <class Epi, class Sched, bool ALIGN_EPI = false, bool SP2 = false, bool ABLK = false, bool BBLK = false>
; __device__ __forceinline__ void gemm_phase(PG8_LAS unsigned char* lds, const Gemm g, const Sched& S, const Epi& E) {
;     ...
;             const char* a1 = cA + (size_t)(t + 1) * kstepA;
;             const char* a2 = last ? nA : cA + (size_t)(t + 2) * kstepA; const char* b2 = last ? nB : cB + (size_t)(t + 2) * kstepB;
;             const char* a3 = a2 + kstepA; const char* b3 = b2 + kstepB;
;     ...
;         for (int a = 0; a < 2; ++a)
; #pragma unroll
;             for (int b = 0; b < 2; ++b)
; #pragma unroll
;                 for (int m = 0; m < 4; ++m)
; #pragma unroll
;                     for (int n = 0; n < 2; ++n) acc[a][b][m][n] = (f32x4){0.f, 0.f, 0.f, 0.f};
.LBB0_304:
	s_add_u32 s0, s0, 0xc000
	s_addc_u32 s1, s1, 0
	s_add_u32 s29, s34, 0x10000
	v_mov_b32_e32 v2, 0
	s_addc_u32 s31, s35, 0
	s_mov_b32 s33, -2
	v_pk_mov_b32 v[2:3], 0, 0
	v_pk_mov_b32 v[4:5], 0, 0
	v_pk_mov_b32 v[6:7], 0, 0
	v_pk_mov_b32 v[8:9], 0, 0
	v_pk_mov_b32 v[10:11], 0, 0
	v_pk_mov_b32 v[12:13], 0, 0
	v_pk_mov_b32 v[14:15], 0, 0
	v_pk_mov_b32 v[16:17], 0, 0
	v_pk_mov_b32 v[18:19], 0, 0
	v_pk_mov_b32 v[20:21], 0, 0
	v_pk_mov_b32 v[22:23], 0, 0
	v_pk_mov_b32 v[24:25], 0, 0
	v_pk_mov_b32 v[26:27], 0, 0
	v_pk_mov_b32 v[28:29], 0, 0
	v_pk_mov_b32 v[30:31], 0, 0
	v_pk_mov_b32 v[32:33], 0, 0
	v_pk_mov_b32 v[34:35], 0, 0
	v_pk_mov_b32 v[36:37], 0, 0
	v_pk_mov_b32 v[38:39], 0, 0
	v_pk_mov_b32 v[40:41], 0, 0
	v_pk_mov_b32 v[42:43], 0, 0
	v_pk_mov_b32 v[44:45], 0, 0
	v_pk_mov_b32 v[46:47], 0, 0
	v_pk_mov_b32 v[48:49], 0, 0
	v_pk_mov_b32 v[50:51], 0, 0
	v_pk_mov_b32 v[52:53], 0, 0
	v_pk_mov_b32 v[54:55], 0, 0
	v_pk_mov_b32 v[56:57], 0, 0
	v_pk_mov_b32 v[58:59], 0, 0
	v_pk_mov_b32 v[60:61], 0, 0
	v_pk_mov_b32 v[62:63], 0, 0
	v_pk_mov_b32 v[64:65], 0, 0
	v_pk_mov_b32 v[66:67], 0, 0
	v_pk_mov_b32 v[68:69], 0, 0
	v_pk_mov_b32 v[70:71], 0, 0
	v_pk_mov_b32 v[72:73], 0, 0
	v_pk_mov_b32 v[74:75], 0, 0
	v_pk_mov_b32 v[76:77], 0, 0
	v_pk_mov_b32 v[78:79], 0, 0
	v_pk_mov_b32 v[80:81], 0, 0
	v_pk_mov_b32 v[82:83], 0, 0
	v_pk_mov_b32 v[84:85], 0, 0
	v_pk_mov_b32 v[86:87], 0, 0
	v_pk_mov_b32 v[88:89], 0, 0
	v_pk_mov_b32 v[90:91], 0, 0
	v_pk_mov_b32 v[92:93], 0, 0
	v_pk_mov_b32 v[94:95], 0, 0
	v_pk_mov_b32 v[96:97], 0, 0
	v_pk_mov_b32 v[98:99], 0, 0
	v_pk_mov_b32 v[100:101], 0, 0
	v_pk_mov_b32 v[102:103], 0, 0
	v_pk_mov_b32 v[104:105], 0, 0
	v_pk_mov_b32 v[106:107], 0, 0
	v_pk_mov_b32 v[108:109], 0, 0
	v_pk_mov_b32 v[110:111], 0, 0
	v_pk_mov_b32 v[112:113], 0, 0
	v_pk_mov_b32 v[114:115], 0, 0
	v_pk_mov_b32 v[116:117], 0, 0
	v_pk_mov_b32 v[118:119], 0, 0
	v_pk_mov_b32 v[120:121], 0, 0
	v_pk_mov_b32 v[122:123], 0, 0
	v_pk_mov_b32 v[124:125], 0, 0
	v_pk_mov_b32 v[126:127], 0, 0
	v_pk_mov_b32 v[128:129], 0, 0

; template <class Epi, class Sched, bool ALIGN_EPI = false, bool SP2 = false, bool ABLK = false, bool BBLK = false>
; __device__ __forceinline__ void gemm_phase(PG8_LAS unsigned char* lds, const Gemm g, const Sched& S, const Epi& E) {
;     ...
;             const char* a1 = cA + (size_t)(t + 1) * kstepA;
;             const char* a2 = last ? nA : cA + (size_t)(t + 2) * kstepA; const char* b2 = last ? nB : cB + (size_t)(t + 2) * kstepB;
;             const char* a3 = a2 + kstepA; const char* b3 = b2 + kstepB;
;     ...
;         for (int a = 0; a < 2; ++a)
; #pragma unroll
;             for (int b = 0; b < 2; ++b)
; #pragma unroll
;                 for (int m = 0; m < 4; ++m)
; #pragma unroll
;                     for (int n = 0; n < 2; ++n) acc[a][b][m][n] = (f32x4){0.f, 0.f, 0.f, 0.f};
.LBB0_366:
	s_add_u32 s0, s0, 0xc000
	s_addc_u32 s1, s1, 0
	s_add_u32 s29, s34, 0x10000
	v_mov_b32_e32 v66, 0
	s_addc_u32 s31, s35, 0
	s_mov_b32 s33, -2
	v_pk_mov_b32 v[2:3], 0, 0
	v_pk_mov_b32 v[4:5], 0, 0
	v_pk_mov_b32 v[6:7], 0, 0
	v_pk_mov_b32 v[8:9], 0, 0
	v_pk_mov_b32 v[10:11], 0, 0
	v_pk_mov_b32 v[12:13], 0, 0
	v_pk_mov_b32 v[14:15], 0, 0
	v_pk_mov_b32 v[16:17], 0, 0
	v_pk_mov_b32 v[18:19], 0, 0
	v_pk_mov_b32 v[20:21], 0, 0
	v_pk_mov_b32 v[22:23], 0, 0
	v_pk_mov_b32 v[24:25], 0, 0
	v_pk_mov_b32 v[34:35], 0, 0
	v_pk_mov_b32 v[36:37], 0, 0
	v_pk_mov_b32 v[38:39], 0, 0
	v_pk_mov_b32 v[40:41], 0, 0
	v_pk_mov_b32 v[42:43], 0, 0
	v_pk_mov_b32 v[44:45], 0, 0
	v_pk_mov_b32 v[46:47], 0, 0
	v_pk_mov_b32 v[48:49], 0, 0
	v_pk_mov_b32 v[50:51], 0, 0
	v_pk_mov_b32 v[52:53], 0, 0
	v_pk_mov_b32 v[54:55], 0, 0
	v_pk_mov_b32 v[56:57], 0, 0
	v_pk_mov_b32 v[58:59], 0, 0
	v_pk_mov_b32 v[60:61], 0, 0
	v_pk_mov_b32 v[62:63], 0, 0
	v_pk_mov_b32 v[64:65], 0, 0
	v_pk_mov_b32 v[66:67], 0, 0
	v_pk_mov_b32 v[68:69], 0, 0
	v_pk_mov_b32 v[70:71], 0, 0
	v_pk_mov_b32 v[72:73], 0, 0
	v_pk_mov_b32 v[74:75], 0, 0
	v_pk_mov_b32 v[76:77], 0, 0
	v_pk_mov_b32 v[78:79], 0, 0
	v_pk_mov_b32 v[80:81], 0, 0
	v_pk_mov_b32 v[82:83], 0, 0
	v_pk_mov_b32 v[84:85], 0, 0
	v_pk_mov_b32 v[86:87], 0, 0
	v_pk_mov_b32 v[88:89], 0, 0
	v_pk_mov_b32 v[90:91], 0, 0
	v_pk_mov_b32 v[92:93], 0, 0
	v_pk_mov_b32 v[94:95], 0, 0
	v_pk_mov_b32 v[96:97], 0, 0
	v_pk_mov_b32 v[98:99], 0, 0
	v_pk_mov_b32 v[100:101], 0, 0
	v_pk_mov_b32 v[102:103], 0, 0
	v_pk_mov_b32 v[104:105], 0, 0
	v_pk_mov_b32 v[106:107], 0, 0
	v_pk_mov_b32 v[108:109], 0, 0
	v_pk_mov_b32 v[110:111], 0, 0
	v_pk_mov_b32 v[112:113], 0, 0
	v_pk_mov_b32 v[114:115], 0, 0
	v_pk_mov_b32 v[116:117], 0, 0
	v_pk_mov_b32 v[118:119], 0, 0
	v_pk_mov_b32 v[120:121], 0, 0
	v_pk_mov_b32 v[122:123], 0, 0
	v_pk_mov_b32 v[124:125], 0, 0
	v_pk_mov_b32 v[126:127], 0, 0
	v_pk_mov_b32 v[128:129], 0, 0
	v_pk_mov_b32 v[130:131], 0, 0
	v_pk_mov_b32 v[132:133], 0, 0
	v_pk_mov_b32 v[134:135], 0, 0
	v_pk_mov_b32 v[136:137], 0, 0

; template <class Epi, class Sched, bool ALIGN_EPI = false, bool SP2 = false, bool ABLK = false, bool BBLK = false>
; __device__ __forceinline__ void gemm_phase(PG8_LAS unsigned char* lds, const Gemm g, const Sched& S, const Epi& E) {
;     ...
;         const char* nA = has_next ? (const char*)g.A + (size_t)nxt.pm * tstepA : cA; const char* nB = has_next ? (const char*)g.Bt + (size_t)nxt.pn * tstepB : cB;
;         for (int t = 0; t < nt; t += 2) {
;             const bool last = (t == nt - 2);
;             const char* a1 = cA + (size_t)(t + 1) * kstepA;
;             const char* a2 = last ? nA : cA + (size_t)(t + 2) * kstepA; const char* b2 = last ? nB : cB + (size_t)(t + 2) * kstepB;
;             const char* a3 = a2 + kstepA; const char* b3 = b2 + kstepB;
;     ...
;         for (int a = 0; a < 2; ++a)
; #pragma unroll
;             for (int b = 0; b < 2; ++b)
; #pragma unroll
;                 for (int m = 0; m < 4; ++m)
; #pragma unroll
;                     for (int n = 0; n < 2; ++n) acc[a][b][m][n] = (f32x4){0.f, 0.f, 0.f, 0.f};
.LBB0_593:
	s_ashr_i32 s21, s20, 31
	s_lshl_b64 s[24:25], s[20:21], 20
	s_add_u32 s24, s51, s24
	s_addc_u32 s25, s53, s25
	s_and_b64 s[26:27], s[6:7], exec
	s_cselect_b32 s9, s25, s1
	s_cselect_b32 s16, s24, s0
	s_ashr_i32 s23, s22, 31
	s_lshl_b64 s[26:27], s[22:23], 20
	s_add_u32 s26, s44, s26
	s_addc_u32 s27, s45, s27
	s_and_b64 s[34:35], s[6:7], exec
	s_cselect_b32 s21, s27, s31
	s_cselect_b32 s23, s26, s30
	s_add_u32 s0, s0, 0xc000
	s_addc_u32 s1, s1, 0
	s_add_u32 s29, s30, 0x10000
	v_mov_b32_e32 v2, 0
	s_addc_u32 s40, s31, 0
	s_mov_b32 s41, -2
	v_mov_b32_e32 v3, v2
	v_mov_b32_e32 v4, v2
	v_mov_b32_e32 v5, v2
	v_mov_b32_e32 v6, v2
	v_mov_b32_e32 v7, v2
	v_mov_b32_e32 v8, v2
	v_mov_b32_e32 v9, v2
	s_waitcnt vmcnt(0)
	v_pk_mov_b32 v[10:11], 0, 0
	v_pk_mov_b32 v[12:13], 0, 0
	v_pk_mov_b32 v[14:15], 0, 0
	v_pk_mov_b32 v[16:17], 0, 0
	v_pk_mov_b32 v[18:19], 0, 0
	v_pk_mov_b32 v[20:21], 0, 0
	v_pk_mov_b32 v[22:23], 0, 0
	v_pk_mov_b32 v[24:25], 0, 0
	v_pk_mov_b32 v[26:27], 0, 0
	v_pk_mov_b32 v[28:29], 0, 0
	v_pk_mov_b32 v[30:31], 0, 0
	v_pk_mov_b32 v[32:33], 0, 0
	v_pk_mov_b32 v[34:35], 0, 0
	v_pk_mov_b32 v[36:37], 0, 0
	v_pk_mov_b32 v[38:39], 0, 0
	v_pk_mov_b32 v[40:41], 0, 0
	v_pk_mov_b32 v[42:43], 0, 0
	v_pk_mov_b32 v[44:45], 0, 0
	v_pk_mov_b32 v[46:47], 0, 0
	v_pk_mov_b32 v[48:49], 0, 0
	v_pk_mov_b32 v[50:51], 0, 0
	v_pk_mov_b32 v[52:53], 0, 0
	v_pk_mov_b32 v[54:55], 0, 0
	v_pk_mov_b32 v[56:57], 0, 0
	v_pk_mov_b32 v[58:59], 0, 0
	v_pk_mov_b32 v[60:61], 0, 0
	v_pk_mov_b32 v[62:63], 0, 0
	v_pk_mov_b32 v[64:65], 0, 0
	v_pk_mov_b32 v[66:67], 0, 0
	v_pk_mov_b32 v[68:69], 0, 0
	v_pk_mov_b32 v[70:71], 0, 0
	v_pk_mov_b32 v[72:73], 0, 0
	v_pk_mov_b32 v[74:75], 0, 0
	v_pk_mov_b32 v[76:77], 0, 0
	v_pk_mov_b32 v[78:79], 0, 0
	v_pk_mov_b32 v[80:81], 0, 0
	v_pk_mov_b32 v[82:83], 0, 0
	v_pk_mov_b32 v[84:85], 0, 0
	v_pk_mov_b32 v[86:87], 0, 0
	v_pk_mov_b32 v[88:89], 0, 0
	v_pk_mov_b32 v[90:91], 0, 0
	v_pk_mov_b32 v[92:93], 0, 0
	v_pk_mov_b32 v[94:95], 0, 0
	v_pk_mov_b32 v[96:97], 0, 0
	v_pk_mov_b32 v[98:99], 0, 0
	v_pk_mov_b32 v[100:101], 0, 0
	v_pk_mov_b32 v[102:103], 0, 0
	v_pk_mov_b32 v[104:105], 0, 0
	v_pk_mov_b32 v[106:107], 0, 0
	v_pk_mov_b32 v[108:109], 0, 0
	v_pk_mov_b32 v[110:111], 0, 0
	v_pk_mov_b32 v[112:113], 0, 0
	v_pk_mov_b32 v[114:115], 0, 0
	v_pk_mov_b32 v[116:117], 0, 0
	v_pk_mov_b32 v[118:119], 0, 0
	v_pk_mov_b32 v[120:121], 0, 0
	v_pk_mov_b32 v[122:123], 0, 0
	v_pk_mov_b32 v[124:125], 0, 0
	v_pk_mov_b32 v[126:127], 0, 0
	v_pk_mov_b32 v[128:129], 0, 0

; template <class Epi, class Sched, bool ALIGN_EPI = false, bool SP2 = false, bool ABLK = false, bool BBLK = false>
; __device__ __forceinline__ void gemm_phase(PG8_LAS unsigned char* lds, const Gemm g, const Sched& S, const Epi& E) {
;     ...
;         const char* nA = has_next ? (const char*)g.A + (size_t)nxt.pm * tstepA : cA; const char* nB = has_next ? (const char*)g.Bt + (size_t)nxt.pn * tstepB : cB;
;         for (int t = 0; t < nt; t += 2) {
;             const bool last = (t == nt - 2);
;             const char* a1 = cA + (size_t)(t + 1) * kstepA;
;             const char* a2 = last ? nA : cA + (size_t)(t + 2) * kstepA; const char* b2 = last ? nB : cB + (size_t)(t + 2) * kstepB;
;             const char* a3 = a2 + kstepA; const char* b3 = b2 + kstepB;
;     ...
;         for (int a = 0; a < 2; ++a)
; #pragma unroll
;             for (int b = 0; b < 2; ++b)
; #pragma unroll
;                 for (int m = 0; m < 4; ++m)
; #pragma unroll
;                     for (int n = 0; n < 2; ++n) acc[a][b][m][n] = (f32x4){0.f, 0.f, 0.f, 0.f};
.LBB0_657:
	s_ashr_i32 s13, s12, 31
	s_lshl_b64 s[14:15], s[12:13], 20
	s_add_u32 s14, s31, s14
	s_addc_u32 s15, s33, s15
	s_and_b64 s[18:19], s[6:7], exec
	s_cselect_b32 s13, s15, s23
	s_cselect_b32 s61, s14, s22
	s_ashr_i32 s1, s0, 31
	s_lshl_b64 s[18:19], s[0:1], 20
	s_add_u32 s18, s51, s18
	s_addc_u32 s19, s53, s19
	s_and_b64 s[26:27], s[6:7], exec
	s_cselect_b32 s1, s19, s25
	s_cselect_b32 s65, s18, s24
	s_add_u32 s22, s22, 0xc000
	s_addc_u32 s23, s23, 0
	s_add_u32 s68, s24, 0x10000
	v_mov_b32_e32 v2, 0
	s_addc_u32 s72, s25, 0
	s_mov_b32 s73, -2
	v_pk_mov_b32 v[2:3], 0, 0
	v_pk_mov_b32 v[4:5], 0, 0
	v_pk_mov_b32 v[6:7], 0, 0
	v_pk_mov_b32 v[8:9], 0, 0
	v_pk_mov_b32 v[10:11], 0, 0
	v_pk_mov_b32 v[12:13], 0, 0
	v_pk_mov_b32 v[14:15], 0, 0
	v_pk_mov_b32 v[16:17], 0, 0
	v_pk_mov_b32 v[18:19], 0, 0
	v_pk_mov_b32 v[20:21], 0, 0
	v_pk_mov_b32 v[22:23], 0, 0
	v_pk_mov_b32 v[24:25], 0, 0
	v_pk_mov_b32 v[26:27], 0, 0
	v_pk_mov_b32 v[28:29], 0, 0
	v_pk_mov_b32 v[30:31], 0, 0
	v_pk_mov_b32 v[32:33], 0, 0
	v_pk_mov_b32 v[34:35], 0, 0
	v_pk_mov_b32 v[36:37], 0, 0
	v_pk_mov_b32 v[38:39], 0, 0
	v_pk_mov_b32 v[40:41], 0, 0
	v_pk_mov_b32 v[42:43], 0, 0
	v_pk_mov_b32 v[44:45], 0, 0
	v_pk_mov_b32 v[46:47], 0, 0
	v_pk_mov_b32 v[48:49], 0, 0
	v_pk_mov_b32 v[50:51], 0, 0
	v_pk_mov_b32 v[52:53], 0, 0
	v_pk_mov_b32 v[54:55], 0, 0
	v_pk_mov_b32 v[56:57], 0, 0
	v_pk_mov_b32 v[58:59], 0, 0
	v_pk_mov_b32 v[60:61], 0, 0
	v_pk_mov_b32 v[62:63], 0, 0
	v_pk_mov_b32 v[64:65], 0, 0
	v_pk_mov_b32 v[66:67], 0, 0
	v_pk_mov_b32 v[68:69], 0, 0
	v_pk_mov_b32 v[70:71], 0, 0
	v_pk_mov_b32 v[72:73], 0, 0
	v_pk_mov_b32 v[74:75], 0, 0
	v_pk_mov_b32 v[76:77], 0, 0
	v_pk_mov_b32 v[78:79], 0, 0
	v_pk_mov_b32 v[80:81], 0, 0
	v_pk_mov_b32 v[82:83], 0, 0
	v_pk_mov_b32 v[84:85], 0, 0
	v_pk_mov_b32 v[86:87], 0, 0
	v_pk_mov_b32 v[88:89], 0, 0
	v_pk_mov_b32 v[90:91], 0, 0
	v_pk_mov_b32 v[92:93], 0, 0
	v_pk_mov_b32 v[94:95], 0, 0
	v_pk_mov_b32 v[96:97], 0, 0
	v_pk_mov_b32 v[98:99], 0, 0
	v_pk_mov_b32 v[100:101], 0, 0
	v_pk_mov_b32 v[102:103], 0, 0
	v_pk_mov_b32 v[104:105], 0, 0
	v_pk_mov_b32 v[106:107], 0, 0
	v_pk_mov_b32 v[108:109], 0, 0
	v_pk_mov_b32 v[110:111], 0, 0
	v_pk_mov_b32 v[112:113], 0, 0
	v_pk_mov_b32 v[114:115], 0, 0
	v_pk_mov_b32 v[116:117], 0, 0
	v_pk_mov_b32 v[118:119], 0, 0
	v_pk_mov_b32 v[120:121], 0, 0
	v_pk_mov_b32 v[122:123], 0, 0
	v_pk_mov_b32 v[124:125], 0, 0
	v_pk_mov_b32 v[126:127], 0, 0
	v_pk_mov_b32 v[128:129], 0, 0

; template <class Epi, class Sched, bool ALIGN_EPI = false, bool SP2 = false, bool ABLK = false, bool BBLK = false>
; __device__ __forceinline__ void gemm_phase(PG8_LAS unsigned char* lds, const Gemm g, const Sched& S, const Epi& E) {
;     ...
;         const char* nA = has_next ? (const char*)g.A + (size_t)nxt.pm * tstepA : cA; const char* nB = has_next ? (const char*)g.Bt + (size_t)nxt.pn * tstepB : cB;
;         for (int t = 0; t < nt; t += 2) {
;             const bool last = (t == nt - 2);
;             const char* a1 = cA + (size_t)(t + 1) * kstepA;
;             const char* a2 = last ? nA : cA + (size_t)(t + 2) * kstepA; const char* b2 = last ? nB : cB + (size_t)(t + 2) * kstepB;
;             const char* a3 = a2 + kstepA; const char* b3 = b2 + kstepB;
;     ...
;         for (int a = 0; a < 2; ++a)
; #pragma unroll
;             for (int b = 0; b < 2; ++b)
; #pragma unroll
;                 for (int m = 0; m < 4; ++m)
; #pragma unroll
;                     for (int n = 0; n < 2; ++n) acc[a][b][m][n] = (f32x4){0.f, 0.f, 0.f, 0.f};
.LBB0_765:
	s_ashr_i32 s15, s14, 31
	s_lshl_b64 s[18:19], s[14:15], 20
	s_add_u32 s18, s33, s18
	s_addc_u32 s19, s34, s19
	s_and_b64 s[20:21], s[6:7], exec
	s_cselect_b32 s1, s19, s25
	s_cselect_b32 s11, s18, s24
	s_ashr_i32 s13, s12, 31
	s_lshl_b64 s[20:21], s[12:13], 20
	s_add_u32 s20, s35, s20
	s_addc_u32 s21, s36, s21
	s_and_b64 s[28:29], s[6:7], exec
	s_cselect_b32 s13, s21, s27
	s_cselect_b32 s15, s20, s26
	s_add_u32 s24, s24, 0x80080
	s_addc_u32 s25, s25, 0
	s_add_u32 s23, s26, 0x100
	v_mov_b32_e32 v2, 0
	s_addc_u32 s65, s27, 0
	s_mov_b32 s68, -2
	v_pk_mov_b32 v[2:3], 0, 0
	v_pk_mov_b32 v[4:5], 0, 0
	v_pk_mov_b32 v[6:7], 0, 0
	v_pk_mov_b32 v[8:9], 0, 0
	v_pk_mov_b32 v[10:11], 0, 0
	v_pk_mov_b32 v[12:13], 0, 0
	v_pk_mov_b32 v[14:15], 0, 0
	v_pk_mov_b32 v[16:17], 0, 0
	v_pk_mov_b32 v[18:19], 0, 0
	v_pk_mov_b32 v[20:21], 0, 0
	v_pk_mov_b32 v[22:23], 0, 0
	v_pk_mov_b32 v[24:25], 0, 0
	v_pk_mov_b32 v[26:27], 0, 0
	v_pk_mov_b32 v[28:29], 0, 0
	v_pk_mov_b32 v[30:31], 0, 0
	v_pk_mov_b32 v[32:33], 0, 0
	v_pk_mov_b32 v[34:35], 0, 0
	v_pk_mov_b32 v[36:37], 0, 0
	v_pk_mov_b32 v[38:39], 0, 0
	v_pk_mov_b32 v[40:41], 0, 0
	v_pk_mov_b32 v[42:43], 0, 0
	v_pk_mov_b32 v[44:45], 0, 0
	v_pk_mov_b32 v[46:47], 0, 0
	v_pk_mov_b32 v[48:49], 0, 0
	v_pk_mov_b32 v[50:51], 0, 0
	v_pk_mov_b32 v[52:53], 0, 0
	v_pk_mov_b32 v[54:55], 0, 0
	v_pk_mov_b32 v[56:57], 0, 0
	v_pk_mov_b32 v[58:59], 0, 0
	v_pk_mov_b32 v[60:61], 0, 0
	v_pk_mov_b32 v[62:63], 0, 0
	v_pk_mov_b32 v[64:65], 0, 0
	v_pk_mov_b32 v[66:67], 0, 0
	v_pk_mov_b32 v[68:69], 0, 0
	v_pk_mov_b32 v[70:71], 0, 0
	v_pk_mov_b32 v[72:73], 0, 0
	v_pk_mov_b32 v[74:75], 0, 0
	v_pk_mov_b32 v[76:77], 0, 0
	v_pk_mov_b32 v[78:79], 0, 0
	v_pk_mov_b32 v[80:81], 0, 0
	v_pk_mov_b32 v[82:83], 0, 0
	v_pk_mov_b32 v[84:85], 0, 0
	v_pk_mov_b32 v[86:87], 0, 0
	v_pk_mov_b32 v[88:89], 0, 0
	v_pk_mov_b32 v[90:91], 0, 0
	v_pk_mov_b32 v[92:93], 0, 0
	v_pk_mov_b32 v[94:95], 0, 0
	v_pk_mov_b32 v[96:97], 0, 0
	v_pk_mov_b32 v[98:99], 0, 0
	v_pk_mov_b32 v[100:101], 0, 0
	v_pk_mov_b32 v[102:103], 0, 0
	v_pk_mov_b32 v[104:105], 0, 0
	v_pk_mov_b32 v[106:107], 0, 0
	v_pk_mov_b32 v[108:109], 0, 0
	v_pk_mov_b32 v[110:111], 0, 0
	v_pk_mov_b32 v[112:113], 0, 0
	v_pk_mov_b32 v[114:115], 0, 0
	v_pk_mov_b32 v[116:117], 0, 0
	v_pk_mov_b32 v[118:119], 0, 0
	v_pk_mov_b32 v[120:121], 0, 0
	v_pk_mov_b32 v[122:123], 0, 0
	v_pk_mov_b32 v[124:125], 0, 0
	v_pk_mov_b32 v[126:127], 0, 0
	v_pk_mov_b32 v[128:129], 0, 0

; template <class Epi, class Sched, bool ALIGN_EPI = false, bool SP2 = false, bool ABLK = false, bool BBLK = false>
; __device__ __forceinline__ void gemm_phase(PG8_LAS unsigned char* lds, const Gemm g, const Sched& S, const Epi& E) {
;     ...
;         const char* nA = has_next ? (const char*)g.A + (size_t)nxt.pm * tstepA : cA; const char* nB = has_next ? (const char*)g.Bt + (size_t)nxt.pn * tstepB : cB;
;         for (int t = 0; t < nt; t += 2) {
;             const bool last = (t == nt - 2);
;             const char* a1 = cA + (size_t)(t + 1) * kstepA;
;             const char* a2 = last ? nA : cA + (size_t)(t + 2) * kstepA; const char* b2 = last ? nB : cB + (size_t)(t + 2) * kstepB;
;             const char* a3 = a2 + kstepA; const char* b3 = b2 + kstepB;
;     ...
;         for (int a = 0; a < 2; ++a)
; #pragma unroll
;             for (int b = 0; b < 2; ++b)
; #pragma unroll
;                 for (int m = 0; m < 4; ++m)
; #pragma unroll
;                     for (int n = 0; n < 2; ++n) acc[a][b][m][n] = (f32x4){0.f, 0.f, 0.f, 0.f};
.LBB0_789:
	s_ashr_i32 s15, s14, 31
	s_lshl_b64 s[18:19], s[14:15], 20
	s_add_u32 s18, s36, s18
	s_addc_u32 s19, s37, s19
	s_and_b64 s[20:21], s[6:7], exec
	s_cselect_b32 s1, s19, s25
	s_cselect_b32 s11, s18, s24
	s_ashr_i32 s13, s12, 31
	s_lshl_b64 s[20:21], s[12:13], 20
	s_add_u32 s20, s44, s20
	s_addc_u32 s21, s45, s21
	s_and_b64 s[28:29], s[6:7], exec
	s_cselect_b32 s13, s21, s27
	s_cselect_b32 s15, s20, s26
	s_add_u32 s24, s24, 0x80080
	s_addc_u32 s25, s25, 0
	s_add_u32 s23, s26, 0x100
	v_mov_b32_e32 v2, 0
	s_addc_u32 s73, s27, 0
	s_mov_b32 s81, -2
	v_pk_mov_b32 v[2:3], 0, 0
	v_pk_mov_b32 v[4:5], 0, 0
	v_pk_mov_b32 v[6:7], 0, 0
	v_pk_mov_b32 v[8:9], 0, 0
	v_pk_mov_b32 v[10:11], 0, 0
	v_pk_mov_b32 v[12:13], 0, 0
	v_pk_mov_b32 v[14:15], 0, 0
	v_pk_mov_b32 v[16:17], 0, 0
	v_pk_mov_b32 v[18:19], 0, 0
	v_pk_mov_b32 v[20:21], 0, 0
	v_pk_mov_b32 v[22:23], 0, 0
	v_pk_mov_b32 v[24:25], 0, 0
	v_pk_mov_b32 v[26:27], 0, 0
	v_pk_mov_b32 v[28:29], 0, 0
	v_pk_mov_b32 v[30:31], 0, 0
	v_pk_mov_b32 v[32:33], 0, 0
	v_pk_mov_b32 v[34:35], 0, 0
	v_pk_mov_b32 v[36:37], 0, 0
	v_pk_mov_b32 v[38:39], 0, 0
	v_pk_mov_b32 v[40:41], 0, 0
	v_pk_mov_b32 v[42:43], 0, 0
	v_pk_mov_b32 v[44:45], 0, 0
	v_pk_mov_b32 v[46:47], 0, 0
	v_pk_mov_b32 v[48:49], 0, 0
	v_pk_mov_b32 v[50:51], 0, 0
	v_pk_mov_b32 v[52:53], 0, 0
	v_pk_mov_b32 v[54:55], 0, 0
	v_pk_mov_b32 v[56:57], 0, 0
	v_pk_mov_b32 v[58:59], 0, 0
	v_pk_mov_b32 v[60:61], 0, 0
	v_pk_mov_b32 v[62:63], 0, 0
	v_pk_mov_b32 v[64:65], 0, 0
	v_pk_mov_b32 v[66:67], 0, 0
	v_pk_mov_b32 v[68:69], 0, 0
	v_pk_mov_b32 v[70:71], 0, 0
	v_pk_mov_b32 v[72:73], 0, 0
	v_pk_mov_b32 v[74:75], 0, 0
	v_pk_mov_b32 v[76:77], 0, 0
	v_pk_mov_b32 v[78:79], 0, 0
	v_pk_mov_b32 v[80:81], 0, 0
	v_pk_mov_b32 v[82:83], 0, 0
	v_pk_mov_b32 v[84:85], 0, 0
	v_pk_mov_b32 v[86:87], 0, 0
	v_pk_mov_b32 v[88:89], 0, 0
	v_pk_mov_b32 v[90:91], 0, 0
	v_pk_mov_b32 v[92:93], 0, 0
	v_pk_mov_b32 v[94:95], 0, 0
	v_pk_mov_b32 v[96:97], 0, 0
	v_pk_mov_b32 v[98:99], 0, 0
	v_pk_mov_b32 v[100:101], 0, 0
	v_pk_mov_b32 v[102:103], 0, 0
	v_pk_mov_b32 v[104:105], 0, 0
	v_pk_mov_b32 v[106:107], 0, 0
	v_pk_mov_b32 v[108:109], 0, 0
	v_pk_mov_b32 v[110:111], 0, 0
	v_pk_mov_b32 v[112:113], 0, 0
	v_pk_mov_b32 v[114:115], 0, 0
	v_pk_mov_b32 v[116:117], 0, 0
	v_pk_mov_b32 v[118:119], 0, 0
	v_pk_mov_b32 v[120:121], 0, 0
	v_pk_mov_b32 v[122:123], 0, 0
	v_pk_mov_b32 v[124:125], 0, 0
	v_pk_mov_b32 v[126:127], 0, 0
	v_pk_mov_b32 v[128:129], 0, 0

; template <class Epi, class Sched, bool ALIGN_EPI = false, bool SP2 = false, bool ABLK = false, bool BBLK = false>
; __device__ __forceinline__ void gemm_phase(PG8_LAS unsigned char* lds, const Gemm g, const Sched& S, const Epi& E) {
;     ...
;         const char* nA = has_next ? (const char*)g.A + (size_t)nxt.pm * tstepA : cA; const char* nB = has_next ? (const char*)g.Bt + (size_t)nxt.pn * tstepB : cB;
;         for (int t = 0; t < nt; t += 2) {
;             const bool last = (t == nt - 2);
;             const char* a1 = cA + (size_t)(t + 1) * kstepA;
;             const char* a2 = last ? nA : cA + (size_t)(t + 2) * kstepA; const char* b2 = last ? nB : cB + (size_t)(t + 2) * kstepB;
;             const char* a3 = a2 + kstepA; const char* b3 = b2 + kstepB;
;     ...
;         for (int a = 0; a < 2; ++a)
; #pragma unroll
;             for (int b = 0; b < 2; ++b)
; #pragma unroll
;                 for (int m = 0; m < 4; ++m)
; #pragma unroll
;                     for (int n = 0; n < 2; ++n) acc[a][b][m][n] = (f32x4){0.f, 0.f, 0.f, 0.f};
.LBB0_814:
	s_ashr_i32 s15, s14, 31
	s_lshl_b64 s[4:5], s[14:15], 17
	s_add_u32 s18, s46, s4
	s_addc_u32 s19, s47, s5
	s_and_b64 s[4:5], s[10:11], exec
	s_cselect_b32 s1, s19, s25
	s_cselect_b32 s9, s18, s24
	s_ashr_i32 s13, s12, 31
	s_lshl_b64 s[4:5], s[12:13], 17
	s_add_u32 s20, s65, s4
	s_addc_u32 s21, s68, s5
	s_and_b64 s[4:5], s[10:11], exec
	v_mov_b32_e32 v2, 0
	s_cselect_b32 s13, s21, s23
	s_cselect_b32 s15, s20, s22
	s_mov_b32 s27, 0
	s_mov_b64 s[28:29], -1
	s_mov_b64 s[30:31], 0
	v_pk_mov_b32 v[2:3], 0, 0
	v_pk_mov_b32 v[4:5], 0, 0
	v_pk_mov_b32 v[6:7], 0, 0
	v_pk_mov_b32 v[8:9], 0, 0
	v_pk_mov_b32 v[10:11], 0, 0
	v_pk_mov_b32 v[12:13], 0, 0
	v_pk_mov_b32 v[14:15], 0, 0
	v_pk_mov_b32 v[16:17], 0, 0
	v_pk_mov_b32 v[18:19], 0, 0
	v_pk_mov_b32 v[20:21], 0, 0
	v_pk_mov_b32 v[22:23], 0, 0
	v_pk_mov_b32 v[24:25], 0, 0
	v_pk_mov_b32 v[26:27], 0, 0
	v_pk_mov_b32 v[28:29], 0, 0
	v_pk_mov_b32 v[30:31], 0, 0
	v_pk_mov_b32 v[32:33], 0, 0
	v_pk_mov_b32 v[34:35], 0, 0
	v_pk_mov_b32 v[36:37], 0, 0
	v_pk_mov_b32 v[38:39], 0, 0
	v_pk_mov_b32 v[40:41], 0, 0
	v_pk_mov_b32 v[42:43], 0, 0
	v_pk_mov_b32 v[44:45], 0, 0
	v_pk_mov_b32 v[46:47], 0, 0
	v_pk_mov_b32 v[48:49], 0, 0
	v_pk_mov_b32 v[50:51], 0, 0
	v_pk_mov_b32 v[52:53], 0, 0
	v_pk_mov_b32 v[54:55], 0, 0
	v_pk_mov_b32 v[56:57], 0, 0
	v_pk_mov_b32 v[58:59], 0, 0
	v_pk_mov_b32 v[60:61], 0, 0
	v_pk_mov_b32 v[62:63], 0, 0
	v_pk_mov_b32 v[64:65], 0, 0
	v_pk_mov_b32 v[66:67], 0, 0
	v_pk_mov_b32 v[68:69], 0, 0
	v_pk_mov_b32 v[70:71], 0, 0
	v_pk_mov_b32 v[72:73], 0, 0
	v_pk_mov_b32 v[74:75], 0, 0
	v_pk_mov_b32 v[76:77], 0, 0
	v_pk_mov_b32 v[78:79], 0, 0
	v_pk_mov_b32 v[80:81], 0, 0
	v_pk_mov_b32 v[82:83], 0, 0
	v_pk_mov_b32 v[84:85], 0, 0
	v_pk_mov_b32 v[86:87], 0, 0
	v_pk_mov_b32 v[88:89], 0, 0
	v_pk_mov_b32 v[90:91], 0, 0
	v_pk_mov_b32 v[92:93], 0, 0
	v_pk_mov_b32 v[94:95], 0, 0
	v_pk_mov_b32 v[96:97], 0, 0
	v_pk_mov_b32 v[98:99], 0, 0
	v_pk_mov_b32 v[100:101], 0, 0
	v_pk_mov_b32 v[102:103], 0, 0
	v_pk_mov_b32 v[104:105], 0, 0
	v_pk_mov_b32 v[106:107], 0, 0
	v_pk_mov_b32 v[108:109], 0, 0
	v_pk_mov_b32 v[110:111], 0, 0
	v_pk_mov_b32 v[112:113], 0, 0
	v_pk_mov_b32 v[114:115], 0, 0
	v_pk_mov_b32 v[116:117], 0, 0
	v_pk_mov_b32 v[118:119], 0, 0
	v_pk_mov_b32 v[120:121], 0, 0
	v_pk_mov_b32 v[122:123], 0, 0
	v_pk_mov_b32 v[124:125], 0, 0
	v_pk_mov_b32 v[126:127], 0, 0
	v_pk_mov_b32 v[128:129], 0, 0

; template <class Epi, class Sched, bool ALIGN_EPI = false, bool SP2 = false, bool ABLK = false, bool BBLK = false>
; __device__ __forceinline__ void gemm_phase(PG8_LAS unsigned char* lds, const Gemm g, const Sched& S, const Epi& E) {
;     ...
;         const char* nA = has_next ? (const char*)g.A + (size_t)nxt.pm * tstepA : cA; const char* nB = has_next ? (const char*)g.Bt + (size_t)nxt.pn * tstepB : cB;
;         for (int t = 0; t < nt; t += 2) {
;             const bool last = (t == nt - 2);
;             const char* a1 = cA + (size_t)(t + 1) * kstepA;
;             const char* a2 = last ? nA : cA + (size_t)(t + 2) * kstepA; const char* b2 = last ? nB : cB + (size_t)(t + 2) * kstepB;
;             const char* a3 = a2 + kstepA; const char* b3 = b2 + kstepB;
;     ...
;         for (int a = 0; a < 2; ++a)
; #pragma unroll
;             for (int b = 0; b < 2; ++b)
; #pragma unroll
;                 for (int m = 0; m < 4; ++m)
; #pragma unroll
;                     for (int n = 0; n < 2; ++n) acc[a][b][m][n] = (f32x4){0.f, 0.f, 0.f, 0.f};
.LBB0_838:
	s_ashr_i32 s13, s12, 31
	s_lshl_b64 s[14:15], s[12:13], 17
	s_add_u32 s14, s44, s14
	s_addc_u32 s15, s45, s15
	s_and_b64 s[18:19], s[8:9], exec
	s_cselect_b32 s1, s15, s23
	s_cselect_b32 s7, s14, s22
	s_ashr_i32 s11, s10, 31
	s_lshl_b64 s[18:19], s[10:11], 17
	s_add_u32 s18, s46, s18
	s_addc_u32 s19, s47, s19
	s_and_b64 s[26:27], s[8:9], exec
	v_mov_b32_e32 v2, 0
	s_cselect_b32 s11, s19, s21
	s_cselect_b32 s13, s18, s20
	s_mov_b32 s25, 0
	s_mov_b64 s[26:27], -1
	s_mov_b64 s[28:29], 0
	v_pk_mov_b32 v[2:3], 0, 0
	v_pk_mov_b32 v[4:5], 0, 0
	v_pk_mov_b32 v[6:7], 0, 0
	v_pk_mov_b32 v[8:9], 0, 0
	v_pk_mov_b32 v[10:11], 0, 0
	v_pk_mov_b32 v[12:13], 0, 0
	v_pk_mov_b32 v[14:15], 0, 0
	v_pk_mov_b32 v[16:17], 0, 0
	v_pk_mov_b32 v[18:19], 0, 0
	v_pk_mov_b32 v[20:21], 0, 0
	v_pk_mov_b32 v[22:23], 0, 0
	v_pk_mov_b32 v[24:25], 0, 0
	v_pk_mov_b32 v[26:27], 0, 0
	v_pk_mov_b32 v[28:29], 0, 0
	v_pk_mov_b32 v[30:31], 0, 0
	v_pk_mov_b32 v[32:33], 0, 0
	v_pk_mov_b32 v[34:35], 0, 0
	v_pk_mov_b32 v[36:37], 0, 0
	v_pk_mov_b32 v[38:39], 0, 0
	v_pk_mov_b32 v[40:41], 0, 0
	v_pk_mov_b32 v[42:43], 0, 0
	v_pk_mov_b32 v[44:45], 0, 0
	v_pk_mov_b32 v[46:47], 0, 0
	v_pk_mov_b32 v[48:49], 0, 0
	v_pk_mov_b32 v[50:51], 0, 0
	v_pk_mov_b32 v[52:53], 0, 0
	v_pk_mov_b32 v[54:55], 0, 0
	v_pk_mov_b32 v[56:57], 0, 0
	v_pk_mov_b32 v[58:59], 0, 0
	v_pk_mov_b32 v[60:61], 0, 0
	v_pk_mov_b32 v[62:63], 0, 0
	v_pk_mov_b32 v[64:65], 0, 0
	v_pk_mov_b32 v[66:67], 0, 0
	v_pk_mov_b32 v[68:69], 0, 0
	v_pk_mov_b32 v[70:71], 0, 0
	v_pk_mov_b32 v[72:73], 0, 0
	v_pk_mov_b32 v[74:75], 0, 0
	v_pk_mov_b32 v[76:77], 0, 0
	v_pk_mov_b32 v[78:79], 0, 0
	v_pk_mov_b32 v[80:81], 0, 0
	v_pk_mov_b32 v[82:83], 0, 0
	v_pk_mov_b32 v[84:85], 0, 0
	v_pk_mov_b32 v[86:87], 0, 0
	v_pk_mov_b32 v[88:89], 0, 0
	v_pk_mov_b32 v[90:91], 0, 0
	v_pk_mov_b32 v[92:93], 0, 0
	v_pk_mov_b32 v[94:95], 0, 0
	v_pk_mov_b32 v[96:97], 0, 0
	v_pk_mov_b32 v[98:99], 0, 0
	v_pk_mov_b32 v[100:101], 0, 0
	v_pk_mov_b32 v[102:103], 0, 0
	v_pk_mov_b32 v[104:105], 0, 0
	v_pk_mov_b32 v[106:107], 0, 0
	v_pk_mov_b32 v[108:109], 0, 0
	v_pk_mov_b32 v[110:111], 0, 0
	v_pk_mov_b32 v[112:113], 0, 0
	v_pk_mov_b32 v[114:115], 0, 0
	v_pk_mov_b32 v[116:117], 0, 0
	v_pk_mov_b32 v[118:119], 0, 0
	v_pk_mov_b32 v[120:121], 0, 0
	v_pk_mov_b32 v[122:123], 0, 0
	v_pk_mov_b32 v[124:125], 0, 0
	v_pk_mov_b32 v[126:127], 0, 0
	v_pk_mov_b32 v[128:129], 0, 0

; template <class Epi, class Sched, bool ALIGN_EPI = false, bool SP2 = false, bool ABLK = false, bool BBLK = false>
; __device__ __forceinline__ void gemm_phase(PG8_LAS unsigned char* lds, const Gemm g, const Sched& S, const Epi& E) {
;     ...
;         const char* nA = has_next ? (const char*)g.A + (size_t)nxt.pm * tstepA : cA; const char* nB = has_next ? (const char*)g.Bt + (size_t)nxt.pn * tstepB : cB;
;         for (int t = 0; t < nt; t += 2) {
;             const bool last = (t == nt - 2);
;             const char* a1 = cA + (size_t)(t + 1) * kstepA;
;             const char* a2 = last ? nA : cA + (size_t)(t + 2) * kstepA; const char* b2 = last ? nB : cB + (size_t)(t + 2) * kstepB;
;             const char* a3 = a2 + kstepA; const char* b3 = b2 + kstepB;
;     ...
;         for (int a = 0; a < 2; ++a)
; #pragma unroll
;             for (int b = 0; b < 2; ++b)
; #pragma unroll
;                 for (int m = 0; m < 4; ++m)
; #pragma unroll
;                     for (int n = 0; n < 2; ++n) acc[a][b][m][n] = (f32x4){0.f, 0.f, 0.f, 0.f};
.LBB0_1116:
	s_ashr_i32 s23, s22, 31
	s_lshl_b64 s[24:25], s[22:23], 18
	s_add_u32 s24, s33, s24
	s_addc_u32 s25, s44, s25
	s_and_b64 s[26:27], s[6:7], exec
	s_cselect_b32 s23, s25, s35
	s_cselect_b32 s31, s24, s34
	s_ashr_i32 s21, s20, 31
	s_lshl_b64 s[26:27], s[20:21], 18
	s_add_u32 s26, s45, s26
	s_addc_u32 s27, s46, s27
	s_and_b64 s[36:37], s[6:7], exec
	s_cselect_b32 s21, s27, s1
	s_cselect_b32 s91, s26, s0
	s_add_u32 s92, s0, 0x10000
	s_addc_u32 s93, s1, 0
	s_add_u32 s0, s34, 0x20080
	v_mov_b32_e32 v2, 0
	s_addc_u32 s1, s35, 0
	s_mov_b32 s94, -2
	v_pk_mov_b32 v[2:3], 0, 0
	v_pk_mov_b32 v[4:5], 0, 0
	v_pk_mov_b32 v[6:7], 0, 0
	v_pk_mov_b32 v[8:9], 0, 0
	v_pk_mov_b32 v[10:11], 0, 0
	v_pk_mov_b32 v[12:13], 0, 0
	v_pk_mov_b32 v[14:15], 0, 0
	v_pk_mov_b32 v[16:17], 0, 0
	v_pk_mov_b32 v[18:19], 0, 0
	v_pk_mov_b32 v[20:21], 0, 0
	v_pk_mov_b32 v[22:23], 0, 0
	v_pk_mov_b32 v[24:25], 0, 0
	v_pk_mov_b32 v[26:27], 0, 0
	v_pk_mov_b32 v[28:29], 0, 0
	v_pk_mov_b32 v[30:31], 0, 0
	v_pk_mov_b32 v[32:33], 0, 0
	v_pk_mov_b32 v[34:35], 0, 0
	v_pk_mov_b32 v[36:37], 0, 0
	v_pk_mov_b32 v[38:39], 0, 0
	v_pk_mov_b32 v[40:41], 0, 0
	v_pk_mov_b32 v[42:43], 0, 0
	v_pk_mov_b32 v[44:45], 0, 0
	v_pk_mov_b32 v[46:47], 0, 0
	v_pk_mov_b32 v[48:49], 0, 0
	v_pk_mov_b32 v[50:51], 0, 0
	v_pk_mov_b32 v[52:53], 0, 0
	v_pk_mov_b32 v[54:55], 0, 0
	v_pk_mov_b32 v[56:57], 0, 0
	v_pk_mov_b32 v[58:59], 0, 0
	v_pk_mov_b32 v[60:61], 0, 0
	v_pk_mov_b32 v[62:63], 0, 0
	v_pk_mov_b32 v[64:65], 0, 0
	v_pk_mov_b32 v[66:67], 0, 0
	v_pk_mov_b32 v[68:69], 0, 0
	v_pk_mov_b32 v[70:71], 0, 0
	v_pk_mov_b32 v[72:73], 0, 0
	v_pk_mov_b32 v[74:75], 0, 0
	v_pk_mov_b32 v[76:77], 0, 0
	v_pk_mov_b32 v[78:79], 0, 0
	v_pk_mov_b32 v[80:81], 0, 0
	v_pk_mov_b32 v[82:83], 0, 0
	v_pk_mov_b32 v[84:85], 0, 0
	v_pk_mov_b32 v[86:87], 0, 0
	v_pk_mov_b32 v[88:89], 0, 0
	v_pk_mov_b32 v[90:91], 0, 0
	v_pk_mov_b32 v[92:93], 0, 0
	v_pk_mov_b32 v[94:95], 0, 0
	v_pk_mov_b32 v[96:97], 0, 0
	v_pk_mov_b32 v[98:99], 0, 0
	v_pk_mov_b32 v[100:101], 0, 0
	v_pk_mov_b32 v[102:103], 0, 0
	v_pk_mov_b32 v[104:105], 0, 0
	v_pk_mov_b32 v[106:107], 0, 0
	v_pk_mov_b32 v[108:109], 0, 0
	v_pk_mov_b32 v[110:111], 0, 0
	v_pk_mov_b32 v[112:113], 0, 0
	v_pk_mov_b32 v[114:115], 0, 0
	v_pk_mov_b32 v[116:117], 0, 0
	v_pk_mov_b32 v[118:119], 0, 0
	v_pk_mov_b32 v[120:121], 0, 0
	v_pk_mov_b32 v[122:123], 0, 0
	v_pk_mov_b32 v[124:125], 0, 0
	v_pk_mov_b32 v[126:127], 0, 0
	v_pk_mov_b32 v[128:129], 0, 0

; template <class Epi, class Sched, bool ALIGN_EPI = false, bool SP2 = false, bool ABLK = false, bool BBLK = false>
; __device__ __forceinline__ void gemm_phase(PG8_LAS unsigned char* lds, const Gemm g, const Sched& S, const Epi& E) {
;     ...
;         const char* nA = has_next ? (const char*)g.A + (size_t)nxt.pm * tstepA : cA; const char* nB = has_next ? (const char*)g.Bt + (size_t)nxt.pn * tstepB : cB;
;         for (int t = 0; t < nt; t += 2) {
;             const bool last = (t == nt - 2);
;             const char* a1 = cA + (size_t)(t + 1) * kstepA;
;             const char* a2 = last ? nA : cA + (size_t)(t + 2) * kstepA; const char* b2 = last ? nB : cB + (size_t)(t + 2) * kstepB;
;             const char* a3 = a2 + kstepA; const char* b3 = b2 + kstepB;
;     ...
;         for (int a = 0; a < 2; ++a)
; #pragma unroll
;             for (int b = 0; b < 2; ++b)
; #pragma unroll
;                 for (int m = 0; m < 4; ++m)
; #pragma unroll
;                     for (int n = 0; n < 2; ++n) acc[a][b][m][n] = (f32x4){0.f, 0.f, 0.f, 0.f};
.LBB0_1139:
	s_ashr_i32 s23, s22, 31
	s_lshl_b64 s[24:25], s[22:23], 19
	s_add_u32 s24, s46, s24
	s_addc_u32 s25, s47, s25
	s_and_b64 s[26:27], s[6:7], exec
	s_cselect_b32 s23, s25, s35
	s_cselect_b32 s31, s24, s34
	s_ashr_i32 s21, s20, 31
	s_lshl_b64 s[26:27], s[20:21], 19
	s_add_u32 s26, s33, s26
	s_addc_u32 s27, s44, s27
	s_and_b64 s[36:37], s[6:7], exec
	s_cselect_b32 s21, s27, s1
	s_cselect_b32 s91, s26, s0
	s_add_u32 s92, s0, 0x10000
	s_addc_u32 s93, s1, 0
	s_add_u32 s0, s34, 0x40080
	v_mov_b32_e32 v2, 0
	s_addc_u32 s1, s35, 0
	s_mov_b32 s94, -2
	v_pk_mov_b32 v[2:3], 0, 0
	v_pk_mov_b32 v[4:5], 0, 0
	v_pk_mov_b32 v[6:7], 0, 0
	v_pk_mov_b32 v[8:9], 0, 0
	v_pk_mov_b32 v[10:11], 0, 0
	v_pk_mov_b32 v[12:13], 0, 0
	v_pk_mov_b32 v[14:15], 0, 0
	v_pk_mov_b32 v[16:17], 0, 0
	v_pk_mov_b32 v[18:19], 0, 0
	v_pk_mov_b32 v[20:21], 0, 0
	v_pk_mov_b32 v[22:23], 0, 0
	v_pk_mov_b32 v[24:25], 0, 0
	v_pk_mov_b32 v[26:27], 0, 0
	v_pk_mov_b32 v[28:29], 0, 0
	v_pk_mov_b32 v[30:31], 0, 0
	v_pk_mov_b32 v[32:33], 0, 0
	v_pk_mov_b32 v[34:35], 0, 0
	v_pk_mov_b32 v[36:37], 0, 0
	v_pk_mov_b32 v[38:39], 0, 0
	v_pk_mov_b32 v[40:41], 0, 0
	v_pk_mov_b32 v[42:43], 0, 0
	v_pk_mov_b32 v[44:45], 0, 0
	v_pk_mov_b32 v[46:47], 0, 0
	v_pk_mov_b32 v[48:49], 0, 0
	v_pk_mov_b32 v[50:51], 0, 0
	v_pk_mov_b32 v[52:53], 0, 0
	v_pk_mov_b32 v[54:55], 0, 0
	v_pk_mov_b32 v[56:57], 0, 0
	v_pk_mov_b32 v[58:59], 0, 0
	v_pk_mov_b32 v[60:61], 0, 0
	v_pk_mov_b32 v[62:63], 0, 0
	v_pk_mov_b32 v[64:65], 0, 0
	v_pk_mov_b32 v[66:67], 0, 0
	v_pk_mov_b32 v[68:69], 0, 0
	v_pk_mov_b32 v[70:71], 0, 0
	v_pk_mov_b32 v[72:73], 0, 0
	v_pk_mov_b32 v[74:75], 0, 0
	v_pk_mov_b32 v[76:77], 0, 0
	v_pk_mov_b32 v[78:79], 0, 0
	v_pk_mov_b32 v[80:81], 0, 0
	v_pk_mov_b32 v[82:83], 0, 0
	v_pk_mov_b32 v[84:85], 0, 0
	v_pk_mov_b32 v[86:87], 0, 0
	v_pk_mov_b32 v[88:89], 0, 0
	v_pk_mov_b32 v[90:91], 0, 0
	v_pk_mov_b32 v[92:93], 0, 0
	v_pk_mov_b32 v[94:95], 0, 0
	v_pk_mov_b32 v[96:97], 0, 0
	v_pk_mov_b32 v[98:99], 0, 0
	v_pk_mov_b32 v[100:101], 0, 0
	v_pk_mov_b32 v[102:103], 0, 0
	v_pk_mov_b32 v[104:105], 0, 0
	v_pk_mov_b32 v[106:107], 0, 0
	v_pk_mov_b32 v[108:109], 0, 0
	v_pk_mov_b32 v[110:111], 0, 0
	v_pk_mov_b32 v[112:113], 0, 0
	v_pk_mov_b32 v[114:115], 0, 0
	v_pk_mov_b32 v[116:117], 0, 0
	v_pk_mov_b32 v[118:119], 0, 0
	v_pk_mov_b32 v[120:121], 0, 0
	v_pk_mov_b32 v[122:123], 0, 0
	v_pk_mov_b32 v[124:125], 0, 0
	v_pk_mov_b32 v[126:127], 0, 0
	v_pk_mov_b32 v[128:129], 0, 0

; template <class Epi, class Sched, bool ALIGN_EPI = false, bool SP2 = false, bool ABLK = false, bool BBLK = false>
; __device__ __forceinline__ void gemm_phase(PG8_LAS unsigned char* lds, const Gemm g, const Sched& S, const Epi& E) {
;     ...
;         const char* nA = has_next ? (const char*)g.A + (size_t)nxt.pm * tstepA : cA; const char* nB = has_next ? (const char*)g.Bt + (size_t)nxt.pn * tstepB : cB;
;         for (int t = 0; t < nt; t += 2) {
;             const bool last = (t == nt - 2);
;             const char* a1 = cA + (size_t)(t + 1) * kstepA;
;             const char* a2 = last ? nA : cA + (size_t)(t + 2) * kstepA; const char* b2 = last ? nB : cB + (size_t)(t + 2) * kstepB;
;             const char* a3 = a2 + kstepA; const char* b3 = b2 + kstepB;
;     ...
;         for (int a = 0; a < 2; ++a)
; #pragma unroll
;             for (int b = 0; b < 2; ++b)
; #pragma unroll
;                 for (int m = 0; m < 4; ++m)
; #pragma unroll
;                     for (int n = 0; n < 2; ++n) acc[a][b][m][n] = (f32x4){0.f, 0.f, 0.f, 0.f};
.LBB0_1162:
	s_ashr_i32 s21, s20, 31
	s_lshl_b64 s[22:23], s[20:21], 18
	s_add_u32 s22, s33, s22
	s_addc_u32 s23, s36, s23
	s_and_b64 s[24:25], s[6:7], exec
	s_cselect_b32 s21, s23, s31
	s_cselect_b32 s29, s22, s30
	s_ashr_i32 s19, s18, 31
	s_lshl_b64 s[24:25], s[18:19], 18
	s_add_u32 s24, s37, s24
	s_addc_u32 s25, s44, s25
	s_and_b64 s[34:35], s[6:7], exec
	s_cselect_b32 s19, s25, s1
	s_cselect_b32 s61, s24, s0
	s_add_u32 s83, s0, 0x10000
	s_addc_u32 s84, s1, 0
	s_add_u32 s0, s30, 0x20080
	v_mov_b32_e32 v2, 0
	s_addc_u32 s1, s31, 0
	s_mov_b32 s86, -2
	v_pk_mov_b32 v[2:3], 0, 0
	v_pk_mov_b32 v[4:5], 0, 0
	v_pk_mov_b32 v[6:7], 0, 0
	v_pk_mov_b32 v[8:9], 0, 0
	v_pk_mov_b32 v[10:11], 0, 0
	v_pk_mov_b32 v[12:13], 0, 0
	v_pk_mov_b32 v[14:15], 0, 0
	v_pk_mov_b32 v[16:17], 0, 0
	v_pk_mov_b32 v[18:19], 0, 0
	v_pk_mov_b32 v[20:21], 0, 0
	v_pk_mov_b32 v[22:23], 0, 0
	v_pk_mov_b32 v[24:25], 0, 0
	v_pk_mov_b32 v[26:27], 0, 0
	v_pk_mov_b32 v[28:29], 0, 0
	v_pk_mov_b32 v[30:31], 0, 0
	v_pk_mov_b32 v[32:33], 0, 0
	v_pk_mov_b32 v[34:35], 0, 0
	v_pk_mov_b32 v[36:37], 0, 0
	v_pk_mov_b32 v[38:39], 0, 0
	v_pk_mov_b32 v[40:41], 0, 0
	v_pk_mov_b32 v[42:43], 0, 0
	v_pk_mov_b32 v[44:45], 0, 0
	v_pk_mov_b32 v[46:47], 0, 0
	v_pk_mov_b32 v[48:49], 0, 0
	v_pk_mov_b32 v[50:51], 0, 0
	v_pk_mov_b32 v[52:53], 0, 0
	v_pk_mov_b32 v[54:55], 0, 0
	v_pk_mov_b32 v[56:57], 0, 0
	v_pk_mov_b32 v[58:59], 0, 0
	v_pk_mov_b32 v[60:61], 0, 0
	v_pk_mov_b32 v[62:63], 0, 0
	v_pk_mov_b32 v[64:65], 0, 0
	v_pk_mov_b32 v[66:67], 0, 0
	v_pk_mov_b32 v[68:69], 0, 0
	v_pk_mov_b32 v[70:71], 0, 0
	v_pk_mov_b32 v[72:73], 0, 0
	v_pk_mov_b32 v[74:75], 0, 0
	v_pk_mov_b32 v[76:77], 0, 0
	v_pk_mov_b32 v[78:79], 0, 0
	v_pk_mov_b32 v[80:81], 0, 0
	v_pk_mov_b32 v[82:83], 0, 0
	v_pk_mov_b32 v[84:85], 0, 0
	v_pk_mov_b32 v[86:87], 0, 0
	v_pk_mov_b32 v[88:89], 0, 0
	v_pk_mov_b32 v[90:91], 0, 0
	v_pk_mov_b32 v[92:93], 0, 0
	v_pk_mov_b32 v[94:95], 0, 0
	v_pk_mov_b32 v[96:97], 0, 0
	v_pk_mov_b32 v[98:99], 0, 0
	v_pk_mov_b32 v[100:101], 0, 0
	v_pk_mov_b32 v[102:103], 0, 0
	v_pk_mov_b32 v[104:105], 0, 0
	v_pk_mov_b32 v[106:107], 0, 0
	v_pk_mov_b32 v[108:109], 0, 0
	v_pk_mov_b32 v[110:111], 0, 0
	v_pk_mov_b32 v[112:113], 0, 0
	v_pk_mov_b32 v[114:115], 0, 0
	v_pk_mov_b32 v[116:117], 0, 0
	v_pk_mov_b32 v[118:119], 0, 0
	v_pk_mov_b32 v[120:121], 0, 0
	v_pk_mov_b32 v[122:123], 0, 0
	v_pk_mov_b32 v[124:125], 0, 0
	v_pk_mov_b32 v[126:127], 0, 0
	v_pk_mov_b32 v[128:129], 0, 0

; template <class Epi, class Sched, bool ALIGN_EPI = false, bool SP2 = false, bool ABLK = false, bool BBLK = false>
; __device__ __forceinline__ void gemm_phase(PG8_LAS unsigned char* lds, const Gemm g, const Sched& S, const Epi& E) {
;     ...
;         const char* nA = has_next ? (const char*)g.A + (size_t)nxt.pm * tstepA : cA; const char* nB = has_next ? (const char*)g.Bt + (size_t)nxt.pn * tstepB : cB;
;         for (int t = 0; t < nt; t += 2) {
;             const bool last = (t == nt - 2);
;             const char* a1 = cA + (size_t)(t + 1) * kstepA;
;             const char* a2 = last ? nA : cA + (size_t)(t + 2) * kstepA; const char* b2 = last ? nB : cB + (size_t)(t + 2) * kstepB;
;             const char* a3 = a2 + kstepA; const char* b3 = b2 + kstepB;
;     ...
;         for (int a = 0; a < 2; ++a)
; #pragma unroll
;             for (int b = 0; b < 2; ++b)
; #pragma unroll
;                 for (int m = 0; m < 4; ++m)
; #pragma unroll
;                     for (int n = 0; n < 2; ++n) acc[a][b][m][n] = (f32x4){0.f, 0.f, 0.f, 0.f};
.LBB0_1238:
	s_ashr_i32 s27, s26, 31
	s_lshl_b64 s[28:29], s[26:27], 20
	s_add_u32 s28, s50, s28
	s_addc_u32 s29, s51, s29
	s_and_b64 s[30:31], s[6:7], exec
	s_cselect_b32 s27, s29, s9
	s_cselect_b32 s35, s28, s8
	s_ashr_i32 s25, s24, 31
	s_lshl_b64 s[30:31], s[24:25], 20
	s_add_u32 s30, s53, s30
	s_addc_u32 s31, s56, s31
	s_and_b64 s[40:41], s[6:7], exec
	s_cselect_b32 s25, s31, s1
	s_cselect_b32 s37, s30, s0
	s_add_u32 s60, s0, 0x10000
	s_addc_u32 s61, s1, 0
	s_add_u32 s0, s8, 0x80080
	v_mov_b32_e32 v38, 0
	s_addc_u32 s1, s9, 0
	s_mov_b32 s92, -2
	v_pk_mov_b32 v[2:3], 0, 0
	v_pk_mov_b32 v[4:5], 0, 0
	v_pk_mov_b32 v[6:7], 0, 0
	v_pk_mov_b32 v[8:9], 0, 0
	v_pk_mov_b32 v[10:11], 0, 0
	v_pk_mov_b32 v[12:13], 0, 0
	v_pk_mov_b32 v[14:15], 0, 0
	v_pk_mov_b32 v[16:17], 0, 0
	v_pk_mov_b32 v[18:19], 0, 0
	v_pk_mov_b32 v[20:21], 0, 0
	v_pk_mov_b32 v[22:23], 0, 0
	v_pk_mov_b32 v[24:25], 0, 0
	v_pk_mov_b32 v[26:27], 0, 0
	v_pk_mov_b32 v[28:29], 0, 0
	v_pk_mov_b32 v[30:31], 0, 0
	v_pk_mov_b32 v[32:33], 0, 0
	v_pk_mov_b32 v[34:35], 0, 0
	v_pk_mov_b32 v[36:37], 0, 0
	v_pk_mov_b32 v[38:39], 0, 0
	v_pk_mov_b32 v[40:41], 0, 0
	v_pk_mov_b32 v[42:43], 0, 0
	v_pk_mov_b32 v[44:45], 0, 0
	v_pk_mov_b32 v[46:47], 0, 0
	v_pk_mov_b32 v[48:49], 0, 0
	v_pk_mov_b32 v[50:51], 0, 0
	v_pk_mov_b32 v[52:53], 0, 0
	v_pk_mov_b32 v[54:55], 0, 0
	v_pk_mov_b32 v[56:57], 0, 0
	v_pk_mov_b32 v[58:59], 0, 0
	v_pk_mov_b32 v[60:61], 0, 0
	v_pk_mov_b32 v[62:63], 0, 0
	v_pk_mov_b32 v[64:65], 0, 0
	v_pk_mov_b32 v[66:67], 0, 0
	v_pk_mov_b32 v[68:69], 0, 0
	v_pk_mov_b32 v[70:71], 0, 0
	v_pk_mov_b32 v[72:73], 0, 0
	v_pk_mov_b32 v[74:75], 0, 0
	v_pk_mov_b32 v[76:77], 0, 0
	v_pk_mov_b32 v[78:79], 0, 0
	v_pk_mov_b32 v[80:81], 0, 0
	v_pk_mov_b32 v[82:83], 0, 0
	v_pk_mov_b32 v[84:85], 0, 0
	v_pk_mov_b32 v[86:87], 0, 0
	v_pk_mov_b32 v[88:89], 0, 0
	v_pk_mov_b32 v[90:91], 0, 0
	v_pk_mov_b32 v[92:93], 0, 0
	v_pk_mov_b32 v[94:95], 0, 0
	v_pk_mov_b32 v[96:97], 0, 0
	v_pk_mov_b32 v[98:99], 0, 0
	v_pk_mov_b32 v[100:101], 0, 0
	v_pk_mov_b32 v[102:103], 0, 0
	v_pk_mov_b32 v[104:105], 0, 0
	v_pk_mov_b32 v[106:107], 0, 0
	v_pk_mov_b32 v[108:109], 0, 0
	v_pk_mov_b32 v[110:111], 0, 0
	v_pk_mov_b32 v[112:113], 0, 0
	v_pk_mov_b32 v[114:115], 0, 0
	v_pk_mov_b32 v[116:117], 0, 0
	v_pk_mov_b32 v[118:119], 0, 0
	v_pk_mov_b32 v[120:121], 0, 0
	v_pk_mov_b32 v[130:131], 0, 0
	v_pk_mov_b32 v[132:133], 0, 0
	v_pk_mov_b32 v[134:135], 0, 0
	v_pk_mov_b32 v[136:137], 0, 0

; template <class Epi, class Sched, bool ALIGN_EPI = false, bool SP2 = false, bool ABLK = false, bool BBLK = false>
; __device__ __forceinline__ void gemm_phase(PG8_LAS unsigned char* lds, const Gemm g, const Sched& S, const Epi& E) {
;     ...
;         const char* nA = has_next ? (const char*)g.A + (size_t)nxt.pm * tstepA : cA; const char* nB = has_next ? (const char*)g.Bt + (size_t)nxt.pn * tstepB : cB;
;         for (int t = 0; t < nt; t += 2) {
;             const bool last = (t == nt - 2);
;             const char* a1 = cA + (size_t)(t + 1) * kstepA;
;             const char* a2 = last ? nA : cA + (size_t)(t + 2) * kstepA; const char* b2 = last ? nB : cB + (size_t)(t + 2) * kstepB;
;             const char* a3 = a2 + kstepA; const char* b3 = b2 + kstepB;
;     ...
;         for (int a = 0; a < 2; ++a)
; #pragma unroll
;             for (int b = 0; b < 2; ++b)
; #pragma unroll
;                 for (int m = 0; m < 4; ++m)
; #pragma unroll
;                     for (int n = 0; n < 2; ++n) acc[a][b][m][n] = (f32x4){0.f, 0.f, 0.f, 0.f};
.LBB0_1339:
	s_ashr_i32 s19, s18, 31
	s_lshl_b64 s[20:21], s[18:19], 20
	s_add_u32 s20, s40, s20
	s_addc_u32 s21, s41, s21
	s_and_b64 s[22:23], s[6:7], exec
	s_cselect_b32 s1, s21, s27
	s_cselect_b32 s19, s20, s26
	s_ashr_i32 s15, s14, 31
	s_lshl_b64 s[22:23], s[14:15], 20
	s_add_u32 s22, s42, s22
	s_addc_u32 s23, s43, s23
	s_and_b64 s[30:31], s[6:7], exec
	s_cselect_b32 s15, s23, s29
	s_cselect_b32 s72, s22, s28
	s_add_u32 s26, s26, 0xc000
	s_addc_u32 s27, s27, 0
	s_add_u32 s73, s28, 0x10000
	v_mov_b32_e32 v2, 0
	s_addc_u32 s81, s29, 0
	s_mov_b32 s83, -2
	v_pk_mov_b32 v[2:3], 0, 0
	v_pk_mov_b32 v[4:5], 0, 0
	v_pk_mov_b32 v[6:7], 0, 0
	v_pk_mov_b32 v[8:9], 0, 0
	v_pk_mov_b32 v[10:11], 0, 0
	v_pk_mov_b32 v[12:13], 0, 0
	v_pk_mov_b32 v[14:15], 0, 0
	v_pk_mov_b32 v[16:17], 0, 0
	v_pk_mov_b32 v[18:19], 0, 0
	v_pk_mov_b32 v[20:21], 0, 0
	v_pk_mov_b32 v[22:23], 0, 0
	v_pk_mov_b32 v[24:25], 0, 0
	v_pk_mov_b32 v[26:27], 0, 0
	v_pk_mov_b32 v[28:29], 0, 0
	v_pk_mov_b32 v[30:31], 0, 0
	v_pk_mov_b32 v[32:33], 0, 0
	v_pk_mov_b32 v[34:35], 0, 0
	v_pk_mov_b32 v[36:37], 0, 0
	v_pk_mov_b32 v[38:39], 0, 0
	v_pk_mov_b32 v[40:41], 0, 0
	v_pk_mov_b32 v[42:43], 0, 0
	v_pk_mov_b32 v[44:45], 0, 0
	v_pk_mov_b32 v[46:47], 0, 0
	v_pk_mov_b32 v[48:49], 0, 0
	v_pk_mov_b32 v[50:51], 0, 0
	v_pk_mov_b32 v[52:53], 0, 0
	v_pk_mov_b32 v[54:55], 0, 0
	v_pk_mov_b32 v[56:57], 0, 0
	v_pk_mov_b32 v[58:59], 0, 0
	v_pk_mov_b32 v[60:61], 0, 0
	v_pk_mov_b32 v[62:63], 0, 0
	v_pk_mov_b32 v[64:65], 0, 0
	v_pk_mov_b32 v[66:67], 0, 0
	v_pk_mov_b32 v[68:69], 0, 0
	v_pk_mov_b32 v[70:71], 0, 0
	v_pk_mov_b32 v[72:73], 0, 0
	v_pk_mov_b32 v[74:75], 0, 0
	v_pk_mov_b32 v[76:77], 0, 0
	v_pk_mov_b32 v[78:79], 0, 0
	v_pk_mov_b32 v[80:81], 0, 0
	v_pk_mov_b32 v[82:83], 0, 0
	v_pk_mov_b32 v[84:85], 0, 0
	v_pk_mov_b32 v[86:87], 0, 0
	v_pk_mov_b32 v[88:89], 0, 0
	v_pk_mov_b32 v[90:91], 0, 0
	v_pk_mov_b32 v[92:93], 0, 0
	v_pk_mov_b32 v[94:95], 0, 0
	v_pk_mov_b32 v[96:97], 0, 0
	v_pk_mov_b32 v[98:99], 0, 0
	v_pk_mov_b32 v[100:101], 0, 0
	v_pk_mov_b32 v[102:103], 0, 0
	v_pk_mov_b32 v[104:105], 0, 0
	v_pk_mov_b32 v[106:107], 0, 0
	v_pk_mov_b32 v[108:109], 0, 0
	v_pk_mov_b32 v[110:111], 0, 0
	v_pk_mov_b32 v[112:113], 0, 0
	v_pk_mov_b32 v[114:115], 0, 0
	v_pk_mov_b32 v[116:117], 0, 0
	v_pk_mov_b32 v[118:119], 0, 0
	v_pk_mov_b32 v[120:121], 0, 0
	v_pk_mov_b32 v[122:123], 0, 0
	v_pk_mov_b32 v[124:125], 0, 0
	v_pk_mov_b32 v[126:127], 0, 0
	v_pk_mov_b32 v[128:129], 0, 0

; template <class Epi, class Sched, bool ALIGN_EPI = false, bool SP2 = false, bool ABLK = false, bool BBLK = false>
; __device__ __forceinline__ void gemm_phase(PG8_LAS unsigned char* lds, const Gemm g, const Sched& S, const Epi& E) {
;     ...
;             const char* a1 = cA + (size_t)(t + 1) * kstepA;
;             const char* a2 = last ? nA : cA + (size_t)(t + 2) * kstepA; const char* b2 = last ? nB : cB + (size_t)(t + 2) * kstepB;
;             const char* a3 = a2 + kstepA; const char* b3 = b2 + kstepB;
;     ...
;         for (int a = 0; a < 2; ++a)
; #pragma unroll
;             for (int b = 0; b < 2; ++b)
; #pragma unroll
;                 for (int m = 0; m < 4; ++m)
; #pragma unroll
;                     for (int n = 0; n < 2; ++n) acc[a][b][m][n] = (f32x4){0.f, 0.f, 0.f, 0.f};
.LBB0_1419:
	s_add_u32 s0, s0, 0xc000
	s_addc_u32 s1, s1, 0
	s_add_u32 s23, s26, 0x10000
	v_mov_b32_e32 v2, 0
	s_addc_u32 s25, s27, 0
	s_mov_b32 s73, -2
	v_pk_mov_b32 v[2:3], 0, 0
	v_pk_mov_b32 v[4:5], 0, 0
	v_pk_mov_b32 v[6:7], 0, 0
	v_pk_mov_b32 v[8:9], 0, 0
	v_pk_mov_b32 v[10:11], 0, 0
	v_pk_mov_b32 v[12:13], 0, 0
	v_pk_mov_b32 v[14:15], 0, 0
	v_pk_mov_b32 v[16:17], 0, 0
	v_pk_mov_b32 v[18:19], 0, 0
	v_pk_mov_b32 v[20:21], 0, 0
	v_pk_mov_b32 v[22:23], 0, 0
	v_pk_mov_b32 v[24:25], 0, 0
	v_pk_mov_b32 v[26:27], 0, 0
	v_pk_mov_b32 v[28:29], 0, 0
	v_pk_mov_b32 v[30:31], 0, 0
	v_pk_mov_b32 v[32:33], 0, 0
	v_pk_mov_b32 v[34:35], 0, 0
	v_pk_mov_b32 v[36:37], 0, 0
	v_pk_mov_b32 v[38:39], 0, 0
	v_pk_mov_b32 v[40:41], 0, 0
	v_pk_mov_b32 v[42:43], 0, 0
	v_pk_mov_b32 v[44:45], 0, 0
	v_pk_mov_b32 v[46:47], 0, 0
	v_pk_mov_b32 v[48:49], 0, 0
	v_pk_mov_b32 v[50:51], 0, 0
	v_pk_mov_b32 v[52:53], 0, 0
	v_pk_mov_b32 v[54:55], 0, 0
	v_pk_mov_b32 v[56:57], 0, 0
	v_pk_mov_b32 v[58:59], 0, 0
	v_pk_mov_b32 v[60:61], 0, 0
	v_pk_mov_b32 v[62:63], 0, 0
	v_pk_mov_b32 v[64:65], 0, 0
	v_pk_mov_b32 v[66:67], 0, 0
	v_pk_mov_b32 v[68:69], 0, 0
	v_pk_mov_b32 v[70:71], 0, 0
	v_pk_mov_b32 v[72:73], 0, 0
	v_pk_mov_b32 v[74:75], 0, 0
	v_pk_mov_b32 v[76:77], 0, 0
	v_pk_mov_b32 v[78:79], 0, 0
	v_pk_mov_b32 v[80:81], 0, 0
	v_pk_mov_b32 v[82:83], 0, 0
	v_pk_mov_b32 v[84:85], 0, 0
	v_pk_mov_b32 v[86:87], 0, 0
	v_pk_mov_b32 v[88:89], 0, 0
	v_pk_mov_b32 v[90:91], 0, 0
	v_pk_mov_b32 v[92:93], 0, 0
	v_pk_mov_b32 v[94:95], 0, 0
	v_pk_mov_b32 v[96:97], 0, 0
	v_pk_mov_b32 v[98:99], 0, 0
	v_pk_mov_b32 v[100:101], 0, 0
	v_pk_mov_b32 v[102:103], 0, 0
	v_pk_mov_b32 v[104:105], 0, 0
	v_pk_mov_b32 v[106:107], 0, 0
	v_pk_mov_b32 v[108:109], 0, 0
	v_pk_mov_b32 v[110:111], 0, 0
	v_pk_mov_b32 v[112:113], 0, 0
	v_pk_mov_b32 v[114:115], 0, 0
	v_pk_mov_b32 v[116:117], 0, 0
	v_pk_mov_b32 v[118:119], 0, 0
	v_pk_mov_b32 v[120:121], 0, 0
	v_pk_mov_b32 v[122:123], 0, 0
	v_pk_mov_b32 v[124:125], 0, 0
	v_pk_mov_b32 v[126:127], 0, 0
	v_pk_mov_b32 v[128:129], 0, 0

; template <class Epi, class Sched, bool ALIGN_EPI = false, bool SP2 = false, bool ABLK = false, bool BBLK = false>
; __device__ __forceinline__ void gemm_phase(PG8_LAS unsigned char* lds, const Gemm g, const Sched& S, const Epi& E) {
;     ...
;             const char* a1 = cA + (size_t)(t + 1) * kstepA;
;             const char* a2 = last ? nA : cA + (size_t)(t + 2) * kstepA; const char* b2 = last ? nB : cB + (size_t)(t + 2) * kstepB;
;             const char* a3 = a2 + kstepA; const char* b3 = b2 + kstepB;
;     ...
;         for (int a = 0; a < 2; ++a)
; #pragma unroll
;             for (int b = 0; b < 2; ++b)
; #pragma unroll
;                 for (int m = 0; m < 4; ++m)
; #pragma unroll
;                     for (int n = 0; n < 2; ++n) acc[a][b][m][n] = (f32x4){0.f, 0.f, 0.f, 0.f};
.LBB0_1482:
	s_add_u32 s0, s0, 0xc000
	s_addc_u32 s1, s1, 0
	s_add_u32 s31, s36, 0x10000
	v_mov_b32_e32 v2, 0
	s_addc_u32 s33, s37, 0
	s_mov_b32 s35, -2
	v_pk_mov_b32 v[2:3], 0, 0
	v_pk_mov_b32 v[4:5], 0, 0
	v_pk_mov_b32 v[6:7], 0, 0
	v_pk_mov_b32 v[8:9], 0, 0
	v_pk_mov_b32 v[10:11], 0, 0
	v_pk_mov_b32 v[12:13], 0, 0
	v_pk_mov_b32 v[14:15], 0, 0
	v_pk_mov_b32 v[16:17], 0, 0
	v_pk_mov_b32 v[18:19], 0, 0
	v_pk_mov_b32 v[20:21], 0, 0
	v_pk_mov_b32 v[22:23], 0, 0
	v_pk_mov_b32 v[24:25], 0, 0
	v_pk_mov_b32 v[26:27], 0, 0
	v_pk_mov_b32 v[28:29], 0, 0
	v_pk_mov_b32 v[30:31], 0, 0
	v_pk_mov_b32 v[32:33], 0, 0
	v_pk_mov_b32 v[34:35], 0, 0
	v_pk_mov_b32 v[36:37], 0, 0
	v_pk_mov_b32 v[38:39], 0, 0
	v_pk_mov_b32 v[40:41], 0, 0
	v_pk_mov_b32 v[42:43], 0, 0
	v_pk_mov_b32 v[44:45], 0, 0
	v_pk_mov_b32 v[46:47], 0, 0
	v_pk_mov_b32 v[48:49], 0, 0
	v_pk_mov_b32 v[50:51], 0, 0
	v_pk_mov_b32 v[52:53], 0, 0
	v_pk_mov_b32 v[54:55], 0, 0
	v_pk_mov_b32 v[56:57], 0, 0
	v_pk_mov_b32 v[58:59], 0, 0
	v_pk_mov_b32 v[60:61], 0, 0
	v_pk_mov_b32 v[62:63], 0, 0
	v_pk_mov_b32 v[64:65], 0, 0
	v_pk_mov_b32 v[66:67], 0, 0
	v_pk_mov_b32 v[68:69], 0, 0
	v_pk_mov_b32 v[70:71], 0, 0
	v_pk_mov_b32 v[72:73], 0, 0
	v_pk_mov_b32 v[74:75], 0, 0
	v_pk_mov_b32 v[76:77], 0, 0
	v_pk_mov_b32 v[78:79], 0, 0
	v_pk_mov_b32 v[80:81], 0, 0
	v_pk_mov_b32 v[82:83], 0, 0
	v_pk_mov_b32 v[84:85], 0, 0
	v_pk_mov_b32 v[86:87], 0, 0
	v_pk_mov_b32 v[88:89], 0, 0
	v_pk_mov_b32 v[90:91], 0, 0
	v_pk_mov_b32 v[92:93], 0, 0
	v_pk_mov_b32 v[94:95], 0, 0
	v_pk_mov_b32 v[96:97], 0, 0
	v_pk_mov_b32 v[98:99], 0, 0
	v_pk_mov_b32 v[100:101], 0, 0
	v_pk_mov_b32 v[102:103], 0, 0
	v_pk_mov_b32 v[104:105], 0, 0
	v_pk_mov_b32 v[106:107], 0, 0
	v_pk_mov_b32 v[108:109], 0, 0
	v_pk_mov_b32 v[110:111], 0, 0
	v_pk_mov_b32 v[112:113], 0, 0
	v_pk_mov_b32 v[114:115], 0, 0
	v_pk_mov_b32 v[116:117], 0, 0
	v_pk_mov_b32 v[118:119], 0, 0
	v_pk_mov_b32 v[120:121], 0, 0
	v_pk_mov_b32 v[122:123], 0, 0
	v_pk_mov_b32 v[124:125], 0, 0
	v_pk_mov_b32 v[126:127], 0, 0
	v_pk_mov_b32 v[128:129], 0, 0
